# GEMM phase prologues: all 7 tile stages issued before the first wait (vmcnt(10) then vmcnt(6)), on top of pool+stack version
# speedup vs baseline: 1.0153x; 1.0025x over previous
; #define PG8_STAGE(bufoff, gbase, voff) do { _Pragma("unroll") for (int _i = 0; _i < 2; ++_i) \
;     __builtin_amdgcn_global_load_lds((const unsigned*)((const char*)(gbase) + (voff)[_i]), (LAS unsigned*)(lds + (bufoff) + ldsw + _i * 8192), 16, 0, 0); } while (0)
; #define PG8_WAIT_V(n) asm volatile("s_waitcnt vmcnt(" #n ")" ::: "memory")
; #define PG8_BAR __builtin_amdgcn_s_barrier()
; template <class Epi>
; DI void gemm_phase(LAS unsigned char* lds, const Gemm g, const Epi& E) {
;     ...
;   for (int i = 0; i < 2; ++i) { int R, C; stage_rc(tid * 16 + i * 8192, R, C); const int Rb = (R & ~31) + perm32(R & 31);
;     voffA[i] = (unsigned)(R * lda + C) * 2u; voffB[i] = (unsigned)(Rb * K + C) * 2u; }
;   const size_t kstep = (size_t)(BK * 2);
;   const size_t hstepA = (size_t)HALF * lda * 2, hstepB = (size_t)HALF * K * 2;
;   const size_t tstepA = 2 * hstepA, tstepB = 2 * hstepB;
;   const unsigned ldsw = (unsigned)wid * 1024u;
;   const int aoff = lds_byte(wr * 64 + fr, fq * 8), boff = lds_byte(wc * 32 + fr, fq * 8);
;     ...
;   PG8_STAGE(PG8_SB(0, 0), cB, voffB); PG8_STAGE(PG8_SA(0, 0), cA, voffA); PG8_STAGE(PG8_SB(0, 1), cB + hstepB, voffB); PG8_STAGE(PG8_SA(0, 1), cA + hstepA, voffA);
;   if (wr == 1) PG8_BAR;
;   PG8_WAIT_V(4); PG8_BAR;
;   PG8_STAGE(PG8_SB(1, 0), cB + kstep, voffB); PG8_STAGE(PG8_SA(1, 0), cA + kstep, voffA); PG8_STAGE(PG8_SB(1, 1), cB + hstepB + kstep, voffB);
;   PG8_WAIT_V(6); PG8_BAR;
.LBB0_186:
	v_lshrrev_b32_e32 v20, 1, v18
	v_and_b32_e32 v20, 24, v20
	s_add_u32 s0, s0, 0xee00000
	v_and_b32_e32 v19, 15, v18
	v_lshlrev_b32_e32 v21, 1, v20
	v_lshlrev_b32_e32 v18, 2, v18
	s_sext_i32_i16 s54, s2
	s_addc_u32 s1, s1, 0
	v_lshl_or_b32 v142, s12, 6, v19
	v_lshl_or_b32 v19, v19, 6, v21
	s_lshl_b32 s2, s12, 13
	v_and_b32_e32 v18, 32, v18
	v_bitop3_b32 v21, v19, s2, v18 bitop3:0xde
	s_lshl_b32 s2, s3, 5
	s_and_b32 s12, s2, 0x60
	s_add_i32 m0, s27, 0x18000
	v_lshl_add_u64 v[10:11], v[10:11], 0, s[84:85]
	s_lshl_b32 s2, s12, 7
	global_load_lds_dwordx4 v[10:11], off
	v_lshl_add_u64 v[8:9], v[8:9], 0, s[84:85]
	s_add_i32 m0, s27, 0x1a000
	s_add_i32 s51, s27, 0x8000
	s_add_i32 s52, s27, 0xa000
	v_bitop3_b32 v143, v19, s2, v18 bitop3:0xde
	global_load_lds_dwordx4 v[8:9], off
	v_lshl_add_u64 v[6:7], v[6:7], 0, s[84:85]
	s_mov_b32 m0, s51
	s_add_u32 s2, s36, 0x80080
	global_load_lds_dwordx4 v[6:7], off
	v_lshl_add_u64 v[4:5], v[4:5], 0, s[84:85]
	s_mov_b32 m0, s52
	s_addc_u32 s3, s37, 0
	global_load_lds_dwordx4 v[4:5], off
	s_add_i32 m0, s27, 0x1c000
	v_lshl_add_u64 v[4:5], s[2:3], 0, v[2:3]
	global_load_lds_dwordx4 v[4:5], off
	v_lshl_add_u64 v[4:5], s[2:3], 0, v[132:133]
	s_add_i32 m0, s27, 0x1e000
	v_or_b32_e32 v144, s12, v20
	global_load_lds_dwordx4 v[4:5], off
	v_lshlrev_b32_e32 v4, 15, v16
	v_and_b32_e32 v4, 0xffff0000, v4
	v_lshl_add_u32 v4, v15, 12, v4
	v_and_b32_e32 v5, 1, v16
	v_lshl_or_b32 v4, v5, 6, v4
	v_lshl_add_u32 v138, v17, 1, v4
	v_lshlrev_b32_e32 v4, 15, v12
	v_and_b32_e32 v4, 0xffff0000, v4
	s_waitcnt vmcnt(10)
	s_barrier
	s_waitcnt vmcnt(6)
	v_lshl_add_u32 v4, v13, 12, v4
	v_and_b32_e32 v5, 1, v12
	v_lshl_or_b32 v4, v5, 6, v4
	v_mov_b32_e32 v139, v3
	v_lshl_add_u32 v140, v14, 1, v4
	v_mov_b32_e32 v141, v3
	s_mov_b32 s53, 0
	v_add_u32_e32 v145, 0, v21
	s_barrier

; #define PG8_STAGE(bufoff, gbase, voff) do { _Pragma("unroll") for (int _i = 0; _i < 2; ++_i) \
;     __builtin_amdgcn_global_load_lds((const unsigned*)((const char*)(gbase) + (voff)[_i]), (LAS unsigned*)(lds + (bufoff) + ldsw + _i * 8192), 16, 0, 0); } while (0)
; #define PG8_WAIT_V(n) asm volatile("s_waitcnt vmcnt(" #n ")" ::: "memory")
; #define PG8_BAR __builtin_amdgcn_s_barrier()
; template <class Epi>
; DI void gemm_phase(LAS unsigned char* lds, const Gemm g, const Epi& E) {
;     ...
;   for (int i = 0; i < 2; ++i) { int R, C; stage_rc(tid * 16 + i * 8192, R, C); const int Rb = (R & ~31) + perm32(R & 31);
;     voffA[i] = (unsigned)(R * lda + C) * 2u; voffB[i] = (unsigned)(Rb * K + C) * 2u; }
;   const size_t kstep = (size_t)(BK * 2);
;   const size_t hstepA = (size_t)HALF * lda * 2, hstepB = (size_t)HALF * K * 2;
;   const size_t tstepA = 2 * hstepA, tstepB = 2 * hstepB;
;   const unsigned ldsw = (unsigned)wid * 1024u;
;   const int aoff = lds_byte(wr * 64 + fr, fq * 8), boff = lds_byte(wc * 32 + fr, fq * 8);
;     ...
;   PG8_STAGE(PG8_SB(0, 0), cB, voffB); PG8_STAGE(PG8_SA(0, 0), cA, voffA); PG8_STAGE(PG8_SB(0, 1), cB + hstepB, voffB); PG8_STAGE(PG8_SA(0, 1), cA + hstepA, voffA);
;   if (wr == 1) PG8_BAR;
;   PG8_WAIT_V(4); PG8_BAR;
;   PG8_STAGE(PG8_SB(1, 0), cB + kstep, voffB); PG8_STAGE(PG8_SA(1, 0), cA + kstep, voffA); PG8_STAGE(PG8_SB(1, 1), cB + hstepB + kstep, voffB);
;   PG8_WAIT_V(6); PG8_BAR;
.LBB0_218:
	s_add_u32 s0, s22, 0xee00000
	s_addc_u32 s1, s23, 0
	s_add_u32 s2, s22, 0x12e00000
	s_addc_u32 s3, s23, 0
	s_add_u32 s12, s22, 0x1ee00000
	s_addc_u32 s13, s23, 0
	s_and_b32 s26, s19, 3
	s_add_i32 m0, s55, 0x18000
	v_lshl_add_u64 v[10:11], v[10:11], 0, s[84:85]
	s_lshl_b32 s59, s18, 6
	s_lshl_b32 s27, s18, 13
	s_lshl_b32 s30, s26, 12
	global_load_lds_dwordx4 v[10:11], off
	v_lshl_add_u64 v[8:9], v[8:9], 0, s[84:85]
	s_add_i32 m0, s55, 0x1a000
	s_add_i32 s60, s55, 0x8000
	s_add_i32 s61, s55, 0xa000
	global_load_lds_dwordx4 v[8:9], off
	v_lshl_add_u64 v[6:7], v[6:7], 0, s[84:85]
	s_mov_b32 m0, s60
	s_add_u32 s18, s44, 0x80080
	global_load_lds_dwordx4 v[6:7], off
	v_lshl_add_u64 v[4:5], v[4:5], 0, s[84:85]
	s_mov_b32 m0, s61
	s_addc_u32 s19, s45, 0
	global_load_lds_dwordx4 v[4:5], off
	s_add_i32 m0, s55, 0x1c000
	v_lshl_add_u64 v[4:5], s[18:19], 0, v[136:137]
	global_load_lds_dwordx4 v[4:5], off
	v_lshl_add_u64 v[4:5], s[18:19], 0, v[132:133]
	s_add_i32 m0, s55, 0x1e000
	v_and_b32_e32 v150, 15, v2
	global_load_lds_dwordx4 v[4:5], off
	v_bfe_u32 v4, v2, 4, 2
	v_lshlrev_b32_e32 v6, 4, v4
	v_lshlrev_b32_e32 v2, 2, v2
	v_lshl_or_b32 v6, v150, 6, v6
	v_and_b32_e32 v2, 32, v2
	v_bitop3_b32 v7, v6, s27, v2 bitop3:0xde
	v_bitop3_b32 v151, v6, s30, v2 bitop3:0xde
	v_lshlrev_b32_e32 v2, 9, v4
	v_lshlrev_b32_e32 v5, 3, v4
	v_lshl_or_b32 v152, s26, 11, v2
	v_lshlrev_b32_e32 v2, 5, v4
	s_cmp_eq_u32 s26, 0
	v_lshl_or_b32 v153, s26, 5, v5
	v_lshl_add_u64 v[4:5], s[22:23], 0, v[2:3]
	s_mov_b64 s[26:27], 0x6600000
	v_lshlrev_b32_e32 v2, 1, v150
	v_lshl_add_u64 v[140:141], v[4:5], 0, s[26:27]
	v_lshl_add_u64 v[4:5], s[22:23], 0, v[2:3]
	v_lshlrev_b32_e32 v2, 15, v16
	s_mov_b64 s[22:23], 0x16e00000
	v_and_b32_e32 v2, 0xffff0000, v2
	v_lshl_add_u64 v[142:143], v[4:5], 0, s[22:23]
	v_lshl_add_u32 v2, v15, 12, v2
	v_and_b32_e32 v4, 1, v16
	v_lshl_or_b32 v2, v4, 6, v2
	v_lshl_add_u32 v144, v17, 1, v2
	v_lshlrev_b32_e32 v2, 15, v12
	v_and_b32_e32 v2, 0xffff0000, v2
	s_waitcnt vmcnt(10)
	s_barrier
	s_waitcnt vmcnt(6)
	v_lshl_add_u32 v2, v13, 12, v2
	v_and_b32_e32 v4, 1, v12
	v_lshl_or_b32 v2, v4, 6, v2
	s_sext_i32_i16 s62, s8
	s_mov_b32 s8, 0
	s_cselect_b64 s[18:19], -1, 0
	v_mov_b32_e32 v145, v3
	v_lshl_add_u32 v146, v14, 1, v2
	v_mov_b32_e32 v147, v3
	v_add_u32_e32 v154, 0, v7
	s_barrier
	s_waitcnt vmcnt(0)
	s_branch .LBB0_222

; DI int fresh_bid() { int t = blockIdx.x; asm volatile("" : "+s"(t)); return t; }
; #define PG8_STAGE(bufoff, gbase, voff) do { _Pragma("unroll") for (int _i = 0; _i < 2; ++_i) \
;     __builtin_amdgcn_global_load_lds((const unsigned*)((const char*)(gbase) + (voff)[_i]), (LAS unsigned*)(lds + (bufoff) + ldsw + _i * 8192), 16, 0, 0); } while (0)
; #define PG8_WAIT_V(n) asm volatile("s_waitcnt vmcnt(" #n ")" ::: "memory")
; #define PG8_BAR __builtin_amdgcn_s_barrier()
; template <class Epi>
; DI void gemm_phase(LAS unsigned char* lds, const Gemm g, const Epi& E) {
;     ...
;   const int K = g.K, nt = K / BK, lda = g.lda;
;   StaticOrder S; S.init(g.nM, g.nN, (int)gridDim.x, fresh_bid());
;   unsigned voffA[2], voffB[2];
; #pragma unroll
;   for (int i = 0; i < 2; ++i) { int R, C; stage_rc(tid * 16 + i * 8192, R, C); const int Rb = (R & ~31) + perm32(R & 31);
;     voffA[i] = (unsigned)(R * lda + C) * 2u; voffB[i] = (unsigned)(Rb * K + C) * 2u; }
;   const size_t kstep = (size_t)(BK * 2);
;   const size_t hstepA = (size_t)HALF * lda * 2, hstepB = (size_t)HALF * K * 2;
;   const size_t tstepA = 2 * hstepA, tstepB = 2 * hstepB;
;   const unsigned ldsw = (unsigned)wid * 1024u;
;   const int aoff = lds_byte(wr * 64 + fr, fq * 8), boff = lds_byte(wc * 32 + fr, fq * 8);
;     ...
;   PG8_STAGE(PG8_SB(0, 0), cB, voffB); PG8_STAGE(PG8_SA(0, 0), cA, voffA); PG8_STAGE(PG8_SB(0, 1), cB + hstepB, voffB); PG8_STAGE(PG8_SA(0, 1), cA + hstepA, voffA);
;   if (wr == 1) PG8_BAR;
;   PG8_WAIT_V(4); PG8_BAR;
;   PG8_STAGE(PG8_SB(1, 0), cB + kstep, voffB); PG8_STAGE(PG8_SA(1, 0), cA + kstep, voffA); PG8_STAGE(PG8_SB(1, 1), cB + hstepB + kstep, voffB);
;   PG8_WAIT_V(6); PG8_BAR;
.LBB0_498:
	s_waitcnt lgkmcnt(0)
	s_add_u32 s26, s26, 0x26e00000
	s_addc_u32 s27, s27, 0
	s_add_i32 m0, s64, 0x18000
	v_lshl_add_u64 v[4:5], v[4:5], 0, s[84:85]
	global_load_lds_dwordx4 v[4:5], off
	v_lshl_add_u64 v[4:5], v[6:7], 0, s[84:85]
	s_add_i32 m0, s64, 0x1a000
	s_add_i32 s69, s64, 0x8000
	global_load_lds_dwordx4 v[4:5], off
	v_lshl_add_u64 v[4:5], v[8:9], 0, s[84:85]
	s_mov_b32 m0, s69
	s_add_i32 s71, s64, 0xa000
	global_load_lds_dwordx4 v[4:5], off
	v_lshl_add_u64 v[4:5], v[10:11], 0, s[84:85]
	s_mov_b32 m0, s71
	v_lshrrev_b32_e32 v25, 1, v17
	global_load_lds_dwordx4 v[4:5], off
	s_add_i32 m0, s64, 0x1c000
	v_lshl_add_u64 v[4:5], v[12:13], 0, s[84:85]
	global_load_lds_dwordx4 v[4:5], off
	v_lshl_add_u64 v[4:5], v[14:15], 0, s[84:85]
	s_add_i32 m0, s64, 0x1e000
	v_and_b32_e32 v25, 24, v25
	global_load_lds_dwordx4 v[4:5], off
	v_and_b32_e32 v24, 15, v17
	v_lshlrev_b32_e32 v26, 1, v25
	v_lshlrev_b32_e32 v17, 2, v17
	v_lshl_or_b32 v192, s40, 6, v24
	v_lshl_or_b32 v24, v24, 6, v26
	s_lshl_b32 s36, s40, 13
	v_and_b32_e32 v17, 32, v17
	v_mul_f32_e32 v4, 0x4f7ffffe, v16
	v_bitop3_b32 v26, v24, s36, v17 bitop3:0xde
	s_lshl_b32 s36, s41, 5
	v_cvt_u32_f32_e32 v4, v4
	s_lshr_b32 s68, s30, 6
	s_and_b32 s40, s36, 0x60
	s_lshl_b32 s36, s40, 7
	s_lshl_b64 s[30:31], s[30:31], 1
	s_add_i32 s72, s68, -2
	s_cmp_lg_u64 s[48:49], 0
	v_bitop3_b32 v193, v24, s36, v17 bitop3:0xde
	s_cselect_b64 s[36:37], -1, 0
	s_cmp_lg_u64 s[50:51], 0
	v_readfirstlane_b32 s41, v4
	v_add_u32_e32 v4, v20, v18
	s_cselect_b64 s[46:47], -1, 0
	v_or_b32_e32 v194, s40, v25
	s_sub_i32 s40, 0, s25
	v_add_lshl_u32 v4, v4, v19, 1
	v_mov_b32_e32 v5, v3
	s_waitcnt vmcnt(10)
	s_barrier
	s_waitcnt vmcnt(6)
	s_mul_i32 s40, s40, s41
	v_lshl_add_u64 v[186:187], s[8:9], 0, v[4:5]
	v_add_u32_e32 v4, v23, v21
	s_mul_hi_u32 s40, s41, s40
	v_add_lshl_u32 v4, v4, v22, 1
	s_mov_b32 s73, 0
	s_add_i32 s74, s41, s40
	v_lshl_add_u64 v[188:189], s[8:9], 0, v[4:5]
	v_add_u32_e32 v195, 0, v26
	s_barrier
	s_branch .LBB0_501
